# v70 + softmax segment K/V tile staging (ds_write + next global loads) moved to the segment head
# baseline (speedup 1.0000x reference)
.Lsstage_mid_0:
	s_cmp_ge_i32 s16, s11
	s_cbranch_scc1 .Lsstage_end_0
	s_or_b32 s16, s16, 1
	s_add_i32 s17, s16, s22
	s_sub_i32 s33, s38, s16
	s_cmp_lt_i32 s16, s23
	s_cselect_b32 s16, s17, s33
	s_lshl_b32 s16, s16, 6
	s_ashr_i32 s17, s16, 31
	s_lshl_b64 s[74:75], s[16:17], 8
	s_add_u32 s74, s74, 0x1000
	s_addc_u32 s75, s75, 0
	v_lshl_add_u64 v[240:241], v[170:171], 0, s[74:75]
	s_add_u32 s74, s74, 0x2000
	s_addc_u32 s75, s75, 0
	v_lshl_add_u64 v[242:243], v[170:171], 0, s[74:75]
	global_load_dwordx4 v[146:149], v[240:241], off offset:-4096
	global_load_dwordx4 v[150:153], v[240:241], off
	global_load_dwordx4 v[154:157], v[242:243], off offset:-4096
	global_load_dwordx4 v[158:161], v[242:243], off

; template <int D0> __device__ __forceinline__ void pv_one(f32x16& od, int vb, bf16x8 pa0, bf16x8 pa1, bf16x8 pa2, bf16x8 pa3) {
;   const s16x4 l0 = tr_read<v_rd_off(D0, 0, 0)>(vb), h0 = tr_read<v_rd_off(D0, 0, 1)>(vb), l1 = tr_read<v_rd_off(D0, 1, 0)>(vb), h1 = tr_read<v_rd_off(D0, 1, 1)>(vb);
;   const s16x4 l2 = tr_read<v_rd_off(D0, 2, 0)>(vb), h2 = tr_read<v_rd_off(D0, 2, 1)>(vb), l3 = tr_read<v_rd_off(D0, 3, 0)>(vb), h3 = tr_read<v_rd_off(D0, 3, 1)>(vb);
;   asm volatile("s_waitcnt lgkmcnt(0)" ::: "memory"); SBAR();
;     ...
;   od = __builtin_amdgcn_mfma_f32_32x32x16_bf16(pa0, PK(l0, h0), od, 0, 0, 0);
;   od = __builtin_amdgcn_mfma_f32_32x32x16_bf16(pa1, PK(l1, h1), od, 0, 0, 0);
;   od = __builtin_amdgcn_mfma_f32_32x32x16_bf16(pa2, PK(l2, h2), od, 0, 0, 0);
;   od = __builtin_amdgcn_mfma_f32_32x32x16_bf16(pa3, PK(l3, h3), od, 0, 0, 0);
;     ...
; }
; __device__ __forceinline__ void pv_d0(f32x16* o, int vb, bf16x8 pa0, bf16x8 pa1, bf16x8 pa2, bf16x8 pa3) {
;   pv_one<0>(o[0], vb, pa0, pa1, pa2, pa3); pv_one<1>(o[1], vb, pa0, pa1, pa2, pa3); pv_one<2>(o[2], vb, pa0, pa1, pa2, pa3); pv_one<3>(o[3], vb, pa0, pa1, pa2, pa3);
; }
; __device__ __forceinline__ void qkt_c(f32x16& p0, f32x16& p1, const char* Ks, const bf16x8* qr, const f32x16& negm, int r32, int hi) {
; #pragma unroll
;   for (int d0 = 0; d0 < 4; ++d0) { const int cb = (d0 * 16 + hi * 8) * 2;
;     bf16x8 b0 = *reinterpret_cast<const bf16x8*>(Ks + KSWZ(r32, cb));
;     bf16x8 b1 = *reinterpret_cast<const bf16x8*>(Ks + KSWZ(32 + r32, cb));
;     if (d0 == 0) { p0 = __builtin_amdgcn_mfma_f32_32x32x16_bf16(b0, qr[0], negm, 0, 0, 0); p1 = __builtin_amdgcn_mfma_f32_32x32x16_bf16(b1, qr[0], negm, 0, 0, 0); }
;     else { p0 = __builtin_amdgcn_mfma_f32_32x32x16_bf16(b0, qr[d0], p0, 0, 0, 0); p1 = __builtin_amdgcn_mfma_f32_32x32x16_bf16(b1, qr[d0], p1, 0, 0, 0); } }
; }
; template <int R> __device__ __forceinline__ void bias_r(f32x16& p0, f32x16& p1, float dq, float nslope) {
;   constexpr int C0 = (R & 3) + 8 * (R >> 2);
;   float x0, x1, a0 = p0[R], a1 = p1[R];
;   asm("v_sub_f32_e32 %0, %1, %2" : "=v"(x0) : "n"(__builtin_bit_cast(int, (float)C0)), "v"(dq));
;   asm("v_sub_f32_e32 %0, %1, %2" : "=v"(x1) : "n"(__builtin_bit_cast(int, (float)(C0 + 32))), "v"(dq));
;   asm("v_fma_f32 %0, %1, |%2|, %0" : "+v"(a0) : "v"(nslope), "v"(x0));
;   asm("v_fma_f32 %0, %1, |%2|, %0" : "+v"(a1) : "v"(nslope), "v"(x1));
.LBB0_375:
.LBB0_379:
	s_waitcnt lgkmcnt(0)
	s_barrier
	ds_read_b128 v[114:117], v195 offset:49152
	ds_read_b128 v[212:215], v195 offset:57344
	ds_read_b128 v[216:219], v196 offset:49152
	s_andn2_b64 vcc, exec, s[14:15]
	s_waitcnt lgkmcnt(2)
	v_mfma_f32_32x32x16_bf16 v[98:113], v[114:117], v[130:133], v[82:97]
	ds_read_b128 v[220:223], v196 offset:57344
	s_waitcnt lgkmcnt(2)
	v_mfma_f32_32x32x16_bf16 v[114:129], v[212:215], v[130:133], v[82:97]
	ds_read_b128 v[212:215], v197 offset:49152
	s_waitcnt lgkmcnt(2)
	v_mfma_f32_32x32x16_bf16 v[98:113], v[216:219], v[134:137], v[98:113]
	ds_read_b128 v[216:219], v197 offset:57344
	s_waitcnt lgkmcnt(2)
	v_mfma_f32_32x32x16_bf16 v[114:129], v[220:223], v[134:137], v[114:129]
	ds_read_b128 v[220:223], v198 offset:49152
	s_waitcnt lgkmcnt(2)
	v_mfma_f32_32x32x16_bf16 v[98:113], v[212:215], v[138:141], v[98:113]
	ds_read_b128 v[212:215], v198 offset:57344
	s_waitcnt lgkmcnt(2)
	v_mfma_f32_32x32x16_bf16 v[114:129], v[216:219], v[138:141], v[114:129]
	s_cbranch_vccnz .Lqk_tail_1
	ds_read_b64_tr_b16 v[204:205], v193 offset:0
	ds_read_b64_tr_b16 v[206:207], v193 offset:0x800
	ds_read_b64_tr_b16 v[208:209], v193 offset:0x1000
	ds_read_b64_tr_b16 v[210:211], v193 offset:0x1800
	s_waitcnt lgkmcnt(5)
	v_mfma_f32_32x32x16_bf16 v[98:113], v[220:223], v[142:145], v[98:113]
	s_waitcnt lgkmcnt(4)
	v_mfma_f32_32x32x16_bf16 v[114:129], v[212:215], v[142:145], v[114:129]
	s_add_i32 s46, s47, -1
	s_add_i32 s72, s72, 1
	s_add_i32 s14, s39, -1
	s_cmp_lt_i32 s46, s23
	s_cselect_b32 s14, s72, s14
	s_lshl_b32 s14, s14, 6
	v_cvt_f32_i32_e32 v0, s14
	v_sub_f32_e32 v0, v192, v0
	ds_read_b64_tr_b16 v[212:213], v193 offset:0x2000
	ds_read_b64_tr_b16 v[214:215], v193 offset:0x2800
	ds_read_b64_tr_b16 v[216:217], v193 offset:0x3000
	ds_read_b64_tr_b16 v[218:219], v193 offset:0x3800
	s_waitcnt lgkmcnt(6)
	v_mfma_f32_32x32x16_bf16 v[64:79], v[2:5], v[204:207], v[64:79]
	v_sub_f32_e32 v14, 0, v0
	v_sub_f32_e32 v15, 0x42000000, v0
	v_fma_f32 v98, v81, |v14|, v98
	v_sub_f32_e32 v14, 0x3f800000, v0
	ds_read_b64_tr_b16 v[204:205], v193 offset:0x200
	ds_read_b64_tr_b16 v[206:207], v193 offset:0xa00
	s_waitcnt lgkmcnt(6)
	v_mfma_f32_32x32x16_bf16 v[64:79], v[6:9], v[208:211], v[64:79]
	v_fma_f32 v114, v81, |v15|, v114
	v_sub_f32_e32 v15, 0x42040000, v0
	v_fma_f32 v99, v81, |v14|, v99
	v_sub_f32_e32 v14, 0x40000000, v0
	ds_read_b64_tr_b16 v[208:209], v193 offset:0x1200
	ds_read_b64_tr_b16 v[210:211], v193 offset:0x1a00
	s_waitcnt lgkmcnt(6)
	v_mfma_f32_32x32x16_bf16 v[64:79], v[10:13], v[212:215], v[64:79]
	v_fma_f32 v115, v81, |v15|, v115
	v_sub_f32_e32 v15, 0x42080000, v0
	v_fma_f32 v100, v81, |v14|, v100
	v_sub_f32_e32 v14, 0x40400000, v0
	ds_read_b64_tr_b16 v[212:213], v193 offset:0x2200
	ds_read_b64_tr_b16 v[214:215], v193 offset:0x2a00
	ds_read_b64_tr_b16 v[220:221], v193 offset:0x3200
	ds_read_b64_tr_b16 v[222:223], v193 offset:0x3a00
	s_waitcnt lgkmcnt(8)
	v_mfma_f32_32x32x16_bf16 v[64:79], v[162:165], v[216:219], v[64:79]
	v_fma_f32 v116, v81, |v15|, v116
	v_sub_f32_e32 v15, 0x420c0000, v0
	v_fma_f32 v101, v81, |v14|, v101
	v_sub_f32_e32 v14, 0x41000000, v0
	s_waitcnt lgkmcnt(6)
	v_mfma_f32_32x32x16_bf16 v[48:63], v[2:5], v[204:207], v[48:63]
	v_fma_f32 v117, v81, |v15|, v117
	v_sub_f32_e32 v15, 0x42200000, v0
	v_fma_f32 v102, v81, |v14|, v102
	v_sub_f32_e32 v14, 0x41100000, v0
	ds_read_b64_tr_b16 v[204:205], v193 offset:0x400
	ds_read_b64_tr_b16 v[206:207], v193 offset:0xc00
	s_waitcnt lgkmcnt(6)
	v_mfma_f32_32x32x16_bf16 v[48:63], v[6:9], v[208:211], v[48:63]
	v_fma_f32 v118, v81, |v15|, v118
	v_sub_f32_e32 v15, 0x42240000, v0
	v_fma_f32 v103, v81, |v14|, v103
	v_sub_f32_e32 v14, 0x41200000, v0
	ds_read_b64_tr_b16 v[208:209], v193 offset:0x1400
	ds_read_b64_tr_b16 v[210:211], v193 offset:0x1c00
	s_waitcnt lgkmcnt(6)
	v_mfma_f32_32x32x16_bf16 v[48:63], v[10:13], v[212:215], v[48:63]
	v_fma_f32 v119, v81, |v15|, v119
	v_sub_f32_e32 v15, 0x42280000, v0
	v_fma_f32 v104, v81, |v14|, v104
	v_sub_f32_e32 v14, 0x41300000, v0
	ds_read_b64_tr_b16 v[212:213], v193 offset:0x2400
	ds_read_b64_tr_b16 v[214:215], v193 offset:0x2c00
	ds_read_b64_tr_b16 v[216:217], v193 offset:0x3400
	ds_read_b64_tr_b16 v[218:219], v193 offset:0x3c00
	s_waitcnt lgkmcnt(8)
	v_mfma_f32_32x32x16_bf16 v[48:63], v[162:165], v[220:223], v[48:63]
	v_fma_f32 v120, v81, |v15|, v120
	v_sub_f32_e32 v15, 0x422c0000, v0
	v_fma_f32 v105, v81, |v14|, v105
	v_sub_f32_e32 v14, 0x41800000, v0
	s_waitcnt lgkmcnt(6)
	v_mfma_f32_32x32x16_bf16 v[32:47], v[2:5], v[204:207], v[32:47]
	v_fma_f32 v121, v81, |v15|, v121
	v_sub_f32_e32 v15, 0x42400000, v0
	v_fma_f32 v106, v81, |v14|, v106
	v_sub_f32_e32 v14, 0x41880000, v0
	ds_read_b64_tr_b16 v[204:205], v193 offset:0x600
	ds_read_b64_tr_b16 v[206:207], v193 offset:0xe00
	s_waitcnt lgkmcnt(6)
	v_mfma_f32_32x32x16_bf16 v[32:47], v[6:9], v[208:211], v[32:47]
	v_fma_f32 v122, v81, |v15|, v122
	v_sub_f32_e32 v15, 0x42440000, v0
	v_fma_f32 v107, v81, |v14|, v107
	v_sub_f32_e32 v14, 0x41900000, v0
	ds_read_b64_tr_b16 v[208:209], v193 offset:0x1600
	ds_read_b64_tr_b16 v[210:211], v193 offset:0x1e00
	s_waitcnt lgkmcnt(6)
	v_mfma_f32_32x32x16_bf16 v[32:47], v[10:13], v[212:215], v[32:47]
	v_fma_f32 v123, v81, |v15|, v123
	v_sub_f32_e32 v15, 0x42480000, v0
	v_fma_f32 v108, v81, |v14|, v108
	v_sub_f32_e32 v14, 0x41980000, v0
	ds_read_b64_tr_b16 v[212:213], v193 offset:0x2600
	ds_read_b64_tr_b16 v[214:215], v193 offset:0x2e00
	ds_read_b64_tr_b16 v[220:221], v193 offset:0x3600
	ds_read_b64_tr_b16 v[222:223], v193 offset:0x3e00
	s_waitcnt lgkmcnt(8)
	v_mfma_f32_32x32x16_bf16 v[32:47], v[162:165], v[216:219], v[32:47]
	v_fma_f32 v124, v81, |v15|, v124
	v_sub_f32_e32 v15, 0x424c0000, v0
	v_fma_f32 v109, v81, |v14|, v109
	v_sub_f32_e32 v14, 0x41c00000, v0
	s_waitcnt lgkmcnt(6)
	v_mfma_f32_32x32x16_bf16 v[16:31], v[2:5], v[204:207], v[16:31]
	v_fma_f32 v125, v81, |v15|, v125
	v_sub_f32_e32 v15, 0x42600000, v0
	v_fma_f32 v110, v81, |v14|, v110
	v_sub_f32_e32 v14, 0x41c80000, v0
	s_waitcnt lgkmcnt(4)
	v_mfma_f32_32x32x16_bf16 v[16:31], v[6:9], v[208:211], v[16:31]
	v_fma_f32 v126, v81, |v15|, v126
	v_sub_f32_e32 v15, 0x42640000, v0
	v_fma_f32 v111, v81, |v14|, v111
	v_sub_f32_e32 v14, 0x41d00000, v0
	s_waitcnt lgkmcnt(2)
	v_mfma_f32_32x32x16_bf16 v[16:31], v[10:13], v[212:215], v[16:31]
	v_fma_f32 v127, v81, |v15|, v127
	v_sub_f32_e32 v15, 0x42680000, v0
	v_fma_f32 v112, v81, |v14|, v112
	v_sub_f32_e32 v14, 0x41d80000, v0
	s_waitcnt lgkmcnt(0)
	v_mfma_f32_32x32x16_bf16 v[16:31], v[162:165], v[220:223], v[16:31]
	v_sub_f32_e32 v0, 0x426c0000, v0
	v_fma_f32 v128, v81, |v15|, v128
	v_fma_f32 v113, v81, |v14|, v113
	v_fma_f32 v129, v81, |v0|, v129
	s_barrier
	s_branch .Lafter_bias_1

.Lsstage_mid_1:
	s_cmp_ge_i32 s16, s11
	s_cbranch_scc1 .Lsstage_end_1
	s_add_i32 s17, s16, 1
	s_not_b32 s16, s16
	s_add_i32 s33, s17, s22
	s_add_i32 s16, s38, s16
	s_cmp_lt_i32 s17, s23
	s_cselect_b32 s16, s33, s16
	s_lshl_b32 s16, s16, 6
	s_ashr_i32 s17, s16, 31
	s_lshl_b64 s[72:73], s[16:17], 8
	s_add_u32 s72, s72, 0x1000
	s_addc_u32 s73, s73, 0
	v_lshl_add_u64 v[240:241], v[170:171], 0, s[72:73]
	s_add_u32 s72, s72, 0x2000
	s_addc_u32 s73, s73, 0
	v_lshl_add_u64 v[242:243], v[170:171], 0, s[72:73]
	global_load_dwordx4 v[146:149], v[240:241], off offset:-4096
	global_load_dwordx4 v[150:153], v[240:241], off
	global_load_dwordx4 v[154:157], v[242:243], off offset:-4096
	global_load_dwordx4 v[158:161], v[242:243], off

; __global__ void __launch_bounds__(NWAVES * 64) mega_fwd(Args args) {
	.amdhsa_kernel _Z8mega_fwd4Args
		.amdhsa_group_segment_fixed_size 0
		.amdhsa_private_segment_fixed_size 0
		.amdhsa_kernarg_size 424
		.amdhsa_user_sgpr_count 2
		.amdhsa_user_sgpr_dispatch_ptr 0
		.amdhsa_user_sgpr_queue_ptr 0
		.amdhsa_user_sgpr_kernarg_segment_ptr 1
		.amdhsa_user_sgpr_dispatch_id 0
		.amdhsa_user_sgpr_kernarg_preload_length 0
		.amdhsa_user_sgpr_kernarg_preload_offset 0
		.amdhsa_user_sgpr_private_segment_size 0
		.amdhsa_uses_dynamic_stack 0
		.amdhsa_enable_private_segment 0
		.amdhsa_system_sgpr_workgroup_id_x 1
		.amdhsa_system_sgpr_workgroup_id_y 0
		.amdhsa_system_sgpr_workgroup_id_z 0
		.amdhsa_system_sgpr_workgroup_info 0
		.amdhsa_system_vgpr_workitem_id 2
		.amdhsa_next_free_vgpr 244
		.amdhsa_next_free_sgpr 102
		.amdhsa_accum_offset 244
		.amdhsa_reserve_vcc 1
		.amdhsa_float_round_mode_32 0
		.amdhsa_float_round_mode_16_64 0
		.amdhsa_float_denorm_mode_32 3
		.amdhsa_float_denorm_mode_16_64 3
		.amdhsa_dx10_clamp 1
		.amdhsa_ieee_mode 1
		.amdhsa_fp16_overflow 0
		.amdhsa_tg_split 0
		.amdhsa_exception_fp_ieee_invalid_op 0
		.amdhsa_exception_fp_denorm_src 0
		.amdhsa_exception_fp_ieee_div_zero 0
		.amdhsa_exception_fp_ieee_overflow 0
		.amdhsa_exception_fp_ieee_underflow 0
		.amdhsa_exception_fp_ieee_inexact 0
		.amdhsa_exception_int_div_zero 0
	.end_amdhsa_kernel

; __global__ void __launch_bounds__(NWAVES * 64) mega_fwd(Args args) {
amdhsa.kernels:
  - .agpr_count:     0
    .args:
      - .offset:         0
        .size:           168
        .value_kind:     by_value
      - .offset:         168
        .size:           4
        .value_kind:     hidden_block_count_x
      - .offset:         172
        .size:           4
        .value_kind:     hidden_block_count_y
      - .offset:         176
        .size:           4
        .value_kind:     hidden_block_count_z
      - .offset:         180
        .size:           2
        .value_kind:     hidden_group_size_x
      - .offset:         182
        .size:           2
        .value_kind:     hidden_group_size_y
      - .offset:         184
        .size:           2
        .value_kind:     hidden_group_size_z
      - .offset:         186
        .size:           2
        .value_kind:     hidden_remainder_x
      - .offset:         188
        .size:           2
        .value_kind:     hidden_remainder_y
      - .offset:         190
        .size:           2
        .value_kind:     hidden_remainder_z
      - .offset:         208
        .size:           8
        .value_kind:     hidden_global_offset_x
      - .offset:         216
        .size:           8
        .value_kind:     hidden_global_offset_y
      - .offset:         224
        .size:           8
        .value_kind:     hidden_global_offset_z
      - .offset:         232
        .size:           2
        .value_kind:     hidden_grid_dims
      - .offset:         256
        .size:           8
        .value_kind:     hidden_multigrid_sync_arg
      - .offset:         288
        .size:           4
        .value_kind:     hidden_dynamic_lds_size
    .group_segment_fixed_size: 0
    .kernarg_segment_align: 8
    .kernarg_segment_size: 424
    .language:       OpenCL C
    .language_version:
      - 2
      - 0
    .max_flat_workgroup_size: 512
    .name:           _Z8mega_fwd4Args
    .private_segment_fixed_size: 0
    .sgpr_count:     108
    .sgpr_spill_count: 22
    .symbol:         _Z8mega_fwd4Args.kd
    .uniform_work_group_size: 1
    .uses_dynamic_stack: false
    .vgpr_count:     244
    .vgpr_spill_count: 0
    .wavefront_size: 64
